# weight transposes of the layer-2 FFN matrices moved from phase 0 into the idle tail of phase 9 (blocks 64..255 after their last GEMM tile)
# baseline (speedup 1.0000x reference)
.LBB0_92:
	v_lshl_add_u32 v20, s2, 3, v145
	s_waitcnt lgkmcnt(0)
	s_barrier
	v_writelane_b32 v255, s24, 8
	v_writelane_b32 v255, s25, 9
	v_writelane_b32 v255, s26, 10
	v_writelane_b32 v255, s27, 11
	s_cmp_lg_u32 s70, 0x100
	s_cbranch_scc1 .Lp0_skip
	v_readfirstlane_b32 s73, v20
	v_and_b32_e32 v200, 31, v144
	v_lshlrev_b32_e32 v100, 2, v200
	v_lshrrev_b32_e32 v101, 5, v144
	v_lshlrev_b32_e32 v201, 14, v145
	v_mul_u32_u24_e32 v202, 0x84, v101
	v_add3_u32 v102, v201, v202, v100
	v_and_b32_e32 v200, 7, v144
	v_lshrrev_b32_e32 v105, 3, v144
	v_mul_u32_u24_e32 v202, 0x420, v200
	v_lshlrev_b32_e32 v203, 2, v105
	v_add3_u32 v103, v201, v202, v203
	v_lshlrev_b32_e32 v104, 4, v200
	v_mov_b32_e32 v106, 0x80
	s_mov_b32 s72, s73
	s_cmp_lt_u32 s73, 0x4400
	s_cbranch_scc1 .Lp0_mp_a
	s_add_u32 s72, s73, 0x2c00
	s_cmp_lt_u32 s73, 0x5a00
	s_cbranch_scc1 .Lp0_mp_a
	s_add_u32 s72, s73, 0x4200
.Lp0_mp_a:
	s_cmp_lt_u32 s72, 0x800
	s_cbranch_scc1 .Lp0_m0_a
	s_cmp_lt_u32 s72, 0x1800
	s_cbranch_scc1 .Lp0_m1_a
	s_cmp_lt_u32 s72, 0x4400
	s_cbranch_scc1 .Lp0_m2_a
	s_cmp_lt_u32 s72, 0x7000
	s_cbranch_scc1 .Lp0_m3_a
	s_cmp_lt_u32 s72, 0x8600
	s_cbranch_scc1 .Lp0_m4_a
	s_cmp_lt_u32 s72, 0x9c00
	s_cbranch_scc1 .Lp0_m5_a
	s_cmp_lt_u32 s72, 0xb860
	s_cbranch_scc1 .Lp0_m6_a
	s_sub_u32 s74, s72, 0xb860
	s_mov_b64 s[76:77], s[22:23]
	s_add_u32 s78, s30, 0xe800000
	s_addc_u32 s79, s31, 0
	s_movk_i32 s80, 0x800
	s_movk_i32 s81, 0x800
	s_mov_b32 s82, 0
	s_movk_i32 s83, 0x0
	s_lshr_b32 s84, s74, 6
	s_and_b32 s85, s74, 63
	s_branch .Lp0_dd_a

.Lp0_loop:
	ds_write_b32 v102, v150
	ds_write_b32 v102, v151 offset:264
	ds_write_b32 v102, v152 offset:528
	ds_write_b32 v102, v153 offset:792
	ds_write_b32 v102, v154 offset:1056
	ds_write_b32 v102, v155 offset:1320
	ds_write_b32 v102, v156 offset:1584
	ds_write_b32 v102, v157 offset:1848
	ds_write_b32 v102, v158 offset:2112
	ds_write_b32 v102, v159 offset:2376
	ds_write_b32 v102, v160 offset:2640
	ds_write_b32 v102, v161 offset:2904
	ds_write_b32 v102, v162 offset:3168
	ds_write_b32 v102, v163 offset:3432
	ds_write_b32 v102, v164 offset:3696
	ds_write_b32 v102, v165 offset:3960
	ds_write_b32 v102, v166 offset:4224
	ds_write_b32 v102, v167 offset:4488
	ds_write_b32 v102, v168 offset:4752
	ds_write_b32 v102, v169 offset:5016
	ds_write_b32 v102, v170 offset:5280
	ds_write_b32 v102, v171 offset:5544
	ds_write_b32 v102, v172 offset:5808
	ds_write_b32 v102, v173 offset:6072
	ds_write_b32 v102, v174 offset:6336
	ds_write_b32 v102, v175 offset:6600
	ds_write_b32 v102, v176 offset:6864
	ds_write_b32 v102, v177 offset:7128
	ds_write_b32 v102, v178 offset:7392
	ds_write_b32 v102, v179 offset:7656
	ds_write_b32 v102, v180 offset:7920
	ds_write_b32 v102, v181 offset:8184
	s_add_u32 s73, s73, 0x800
	s_cmp_lt_u32 s73, 0x7e60
	s_cselect_b32 s64, 1, 0
	s_cbranch_scc0 .Lp0_nold
	s_mov_b32 s72, s73
	s_cmp_lt_u32 s73, 0x4400
	s_cbranch_scc1 .Lp0_mp_b
	s_add_u32 s72, s73, 0x2c00
	s_cmp_lt_u32 s73, 0x5a00
	s_cbranch_scc1 .Lp0_mp_b
	s_add_u32 s72, s73, 0x4200

.LBB0_1034:
	s_waitcnt vmcnt(0)
	s_barrier
	s_cmp_lg_u32 s70, 0x100
	s_cbranch_scc1 .Lp9_done
	s_cmp_lt_u32 s2, 64
	s_cbranch_scc1 .Lp9_done
	v_readlane_b32 s6, v255, 8
	v_readlane_b32 s7, v255, 9
	v_readlane_b32 s10, v255, 10
	v_readlane_b32 s11, v255, 11
	v_readfirstlane_b32 s75, v145
	s_sub_u32 s73, s2, 64
	s_lshl_b32 s73, s73, 3
	s_add_u32 s73, s73, s75
	v_and_b32_e32 v200, 31, v144
	v_lshlrev_b32_e32 v100, 2, v200
	v_lshrrev_b32_e32 v101, 5, v144
	v_lshlrev_b32_e32 v201, 14, v145
	v_mul_u32_u24_e32 v202, 0x84, v101
	v_add3_u32 v102, v201, v202, v100
	v_and_b32_e32 v200, 7, v144
	v_lshrrev_b32_e32 v105, 3, v144
	v_mul_u32_u24_e32 v202, 0x420, v200
	v_lshlrev_b32_e32 v203, 2, v105
	v_add3_u32 v103, v201, v202, v203
	v_lshlrev_b32_e32 v104, 4, v200
	v_mov_b32_e32 v106, 0x80
	s_add_u32 s72, s73, 0x4400
	s_cmp_lt_u32 s73, 0x2c00
	s_cbranch_scc1 .Lp9_mp_a
	s_add_u32 s72, s73, 0x5a00
.Lp9_mp_a:
	s_cmp_lt_u32 s72, 0x800
	s_cbranch_scc1 .Lp9_m0_a
	s_cmp_lt_u32 s72, 0x1800
	s_cbranch_scc1 .Lp9_m1_a
	s_cmp_lt_u32 s72, 0x4400
	s_cbranch_scc1 .Lp9_m2_a
	s_cmp_lt_u32 s72, 0x7000
	s_cbranch_scc1 .Lp9_m3_a
	s_cmp_lt_u32 s72, 0x8600
	s_cbranch_scc1 .Lp9_m4_a
	s_cmp_lt_u32 s72, 0x9c00
	s_cbranch_scc1 .Lp9_m5_a
	s_cmp_lt_u32 s72, 0xb860
	s_cbranch_scc1 .Lp9_m6_a
	s_sub_u32 s74, s72, 0xb860
	s_mov_b64 s[76:77], s[22:23]
	s_add_u32 s78, s30, 0xe800000
	s_addc_u32 s79, s31, 0
	s_movk_i32 s80, 0x800
	s_movk_i32 s81, 0x800
	s_mov_b32 s12, 0
	s_movk_i32 s13, 0x0
	s_lshr_b32 s14, s74, 6
	s_and_b32 s15, s74, 63
	s_branch .Lp9_dd_a
.Lp9_m0_a:
	s_mov_b32 s74, s72
	s_mov_b64 s[76:77], s[50:51]
	s_add_u32 s78, s30, 0x2f00000
	s_addc_u32 s79, s31, 0
	s_movk_i32 s80, 0x800
	s_movk_i32 s81, 0x800
	s_mov_b32 s12, 0
	s_movk_i32 s13, 0x0
	s_lshr_b32 s14, s74, 6
	s_and_b32 s15, s74, 63
	s_branch .Lp9_dd_a
.Lp9_m1_a:
	s_sub_u32 s74, s72, 0x800
	s_mov_b64 s[76:77], s[16:17]
	s_add_u32 s78, s30, 0x3700000
	s_addc_u32 s79, s31, 0
	s_movk_i32 s80, 0x800
	s_movk_i32 s81, 0x1000
	s_mov_b32 s12, 1
	s_movk_i32 s13, 0x800
	s_lshr_b32 s14, s74, 7
	s_and_b32 s15, s74, 127
	s_branch .Lp9_dd_a
.Lp9_m2_a:
	s_sub_u32 s74, s72, 0x1800
	s_mov_b64 s[76:77], s[6:7]
	s_add_u32 s78, s30, 0x4700000
	s_addc_u32 s79, s31, 0
	s_movk_i32 s80, 0x800
	s_movk_i32 s81, 0x2c00
	s_mov_b32 s12, 1
	s_movk_i32 s13, 0x1600
	s_mul_hi_u32 s14, s74, 0xba2e8c
	s_mul_i32 s75, s14, 0x160
	s_sub_u32 s15, s74, s75
	s_branch .Lp9_dd_a
.Lp9_m3_a:
	s_sub_u32 s74, s72, 0x4400
	s_add_u32 s76, s6, 0x5800000
	s_addc_u32 s77, s7, 0
	s_add_u32 s78, s30, 0x7300000
	s_addc_u32 s79, s31, 0
	s_movk_i32 s80, 0x800
	s_movk_i32 s81, 0x2c00
	s_mov_b32 s12, 1
	s_movk_i32 s13, 0x1600
	s_mul_hi_u32 s14, s74, 0xba2e8c
	s_mul_i32 s75, s14, 0x160
	s_sub_u32 s15, s74, s75
	s_branch .Lp9_dd_a
.Lp9_m4_a:
	s_sub_u32 s74, s72, 0x7000
	s_mov_b64 s[76:77], s[10:11]
	s_add_u32 s78, s30, 0x9f00000
	s_addc_u32 s79, s31, 0
	s_movk_i32 s80, 0x1600
	s_movk_i32 s81, 0x800
	s_mov_b32 s12, 0
	s_movk_i32 s13, 0x0
	s_lshr_b32 s14, s74, 6
	s_and_b32 s15, s74, 63
	s_branch .Lp9_dd_a
.Lp9_m5_a:
	s_sub_u32 s74, s72, 0x8600
	s_add_u32 s76, s10, 0x2c00000
	s_addc_u32 s77, s11, 0
	s_add_u32 s78, s30, 0xb500000
	s_addc_u32 s79, s31, 0
	s_movk_i32 s80, 0x1600
	s_movk_i32 s81, 0x800
	s_mov_b32 s12, 0
	s_movk_i32 s13, 0x0
	s_lshr_b32 s14, s74, 6
	s_and_b32 s15, s74, 63
	s_branch .Lp9_dd_a
.Lp9_m6_a:
	s_sub_u32 s74, s72, 0x9c00
	s_mov_b64 s[76:77], s[20:21]
	s_add_u32 s78, s30, 0xcb00000
	s_addc_u32 s79, s31, 0
	s_movk_i32 s80, 0x800
	s_movk_i32 s81, 0x1c50
	s_mov_b32 s12, 3
	s_movk_i32 s13, 0x0
	s_mul_hi_u32 s14, s74, 0x120b471
	s_mul_i32 s75, s14, 0xe3
	s_sub_u32 s15, s74, s75
.Lp9_dd_a:
	s_lshl_b32 s86, s15, 5
	s_lshl_b32 s87, s14, 6
	s_mul_i32 s75, s87, s81
	s_add_u32 s75, s75, s86
	s_lshl_b32 s75, s75, 2
	s_add_u32 s88, s76, s75
	s_addc_u32 s89, s77, 0
	s_lshl_b32 s90, s81, 3
	s_lshl_b32 s95, s81, 2
	v_mad_u32_u24 v141, v101, s95, v100
	s_mov_b32 s91, 0
	s_cmp_eq_u32 s12, 3
	s_cbranch_scc0 .Lp9_np_a
	s_cmp_eq_u32 s15, 0xe2
	s_cselect_b32 s91, 1, 0

.Lp9_fl_a:
	global_load_dword v150, v141, s[88:89]
	s_add_u32 s88, s88, s90
	s_addc_u32 s89, s89, 0
	global_load_dword v151, v141, s[88:89]
	s_add_u32 s88, s88, s90
	s_addc_u32 s89, s89, 0
	global_load_dword v152, v141, s[88:89]
	s_add_u32 s88, s88, s90
	s_addc_u32 s89, s89, 0
	global_load_dword v153, v141, s[88:89]
	s_add_u32 s88, s88, s90
	s_addc_u32 s89, s89, 0
	global_load_dword v154, v141, s[88:89]
	s_add_u32 s88, s88, s90
	s_addc_u32 s89, s89, 0
	global_load_dword v155, v141, s[88:89]
	s_add_u32 s88, s88, s90
	s_addc_u32 s89, s89, 0
	global_load_dword v156, v141, s[88:89]
	s_add_u32 s88, s88, s90
	s_addc_u32 s89, s89, 0
	global_load_dword v157, v141, s[88:89]
	s_add_u32 s88, s88, s90
	s_addc_u32 s89, s89, 0
	global_load_dword v158, v141, s[88:89]
	s_add_u32 s88, s88, s90
	s_addc_u32 s89, s89, 0
	global_load_dword v159, v141, s[88:89]
	s_add_u32 s88, s88, s90
	s_addc_u32 s89, s89, 0
	global_load_dword v160, v141, s[88:89]
	s_add_u32 s88, s88, s90
	s_addc_u32 s89, s89, 0
	global_load_dword v161, v141, s[88:89]
	s_add_u32 s88, s88, s90
	s_addc_u32 s89, s89, 0
	global_load_dword v162, v141, s[88:89]
	s_add_u32 s88, s88, s90
	s_addc_u32 s89, s89, 0
	global_load_dword v163, v141, s[88:89]
	s_add_u32 s88, s88, s90
	s_addc_u32 s89, s89, 0
	global_load_dword v164, v141, s[88:89]
	s_add_u32 s88, s88, s90
	s_addc_u32 s89, s89, 0
	global_load_dword v165, v141, s[88:89]
	s_add_u32 s88, s88, s90
	s_addc_u32 s89, s89, 0
	global_load_dword v166, v141, s[88:89]
	s_add_u32 s88, s88, s90
	s_addc_u32 s89, s89, 0
	global_load_dword v167, v141, s[88:89]
	s_add_u32 s88, s88, s90
	s_addc_u32 s89, s89, 0
	global_load_dword v168, v141, s[88:89]
	s_add_u32 s88, s88, s90
	s_addc_u32 s89, s89, 0
	global_load_dword v169, v141, s[88:89]
	s_add_u32 s88, s88, s90
	s_addc_u32 s89, s89, 0
	global_load_dword v170, v141, s[88:89]
	s_add_u32 s88, s88, s90
	s_addc_u32 s89, s89, 0
	global_load_dword v171, v141, s[88:89]
	s_add_u32 s88, s88, s90
	s_addc_u32 s89, s89, 0
	global_load_dword v172, v141, s[88:89]
	s_add_u32 s88, s88, s90
	s_addc_u32 s89, s89, 0
	global_load_dword v173, v141, s[88:89]
	s_add_u32 s88, s88, s90
	s_addc_u32 s89, s89, 0
	global_load_dword v174, v141, s[88:89]
	s_add_u32 s88, s88, s90
	s_addc_u32 s89, s89, 0
	global_load_dword v175, v141, s[88:89]
	s_add_u32 s88, s88, s90
	s_addc_u32 s89, s89, 0
	global_load_dword v176, v141, s[88:89]
	s_add_u32 s88, s88, s90
	s_addc_u32 s89, s89, 0
	global_load_dword v177, v141, s[88:89]
	s_add_u32 s88, s88, s90
	s_addc_u32 s89, s89, 0
	global_load_dword v178, v141, s[88:89]
	s_add_u32 s88, s88, s90
	s_addc_u32 s89, s89, 0
	global_load_dword v179, v141, s[88:89]
	s_add_u32 s88, s88, s90
	s_addc_u32 s89, s89, 0
	global_load_dword v180, v141, s[88:89]
	s_add_u32 s88, s88, s90
	s_addc_u32 s89, s89, 0
	global_load_dword v181, v141, s[88:89]
	s_mov_b64 exec, -1
	s_lshl_b32 s95, s87, 1
	s_add_u32 s92, s78, s95
	s_addc_u32 s93, s79, 0
	s_mov_b32 s94, s91
	s_lshl_b32 s96, s80, 1
	v_mov_b32_e32 v142, s13
	s_cmp_eq_u32 s12, 0
	s_cbranch_scc1 .Lp9_r0_a
	s_cmp_eq_u32 s12, 1
	s_cbranch_scc1 .Lp9_r1_a
	s_cmp_lt_u32 s86, 0x1000
	s_cbranch_scc1 .Lp9_r3a_a
	s_cmp_lt_u32 s86, 0x1800
	s_cbranch_scc1 .Lp9_r0_a
	s_cmp_lt_u32 s86, 0x1c00
	s_cbranch_scc1 .Lp9_r3c_a
	s_add_u32 s95, s86, 0
	v_add_u32_e32 v143, s95, v105
	v_add_u32_e32 v200, 0xffffe3f0, v143
	v_and_b32_e32 v201, 32, v200
	v_lshlrev_b32_e32 v201, 2, v201
	v_and_b32_e32 v200, 31, v200
	v_add_u32_e32 v200, 0x1c00, v200
	v_add_u32_e32 v200, v200, v201
	v_mov_b32_e32 v202, 0x1c10
	v_cmp_gt_u32_e32 vcc, v202, v143
	v_add_u32_e32 v201, 32, v143
	s_nop 0
	v_cndmask_b32_e32 v203, v200, v201, vcc
	v_mad_u32_u24 v108, v203, s96, v104
	s_add_u32 s95, s86, 8
	v_add_u32_e32 v143, s95, v105
	v_add_u32_e32 v200, 0xffffe3f0, v143
	v_and_b32_e32 v201, 32, v200
	v_lshlrev_b32_e32 v201, 2, v201
	v_and_b32_e32 v200, 31, v200
	v_add_u32_e32 v200, 0x1c00, v200
	v_add_u32_e32 v200, v200, v201
	v_mov_b32_e32 v202, 0x1c10
	v_cmp_gt_u32_e32 vcc, v202, v143
	v_add_u32_e32 v201, 32, v143
	s_nop 0
	v_cndmask_b32_e32 v203, v200, v201, vcc
	v_mad_u32_u24 v109, v203, s96, v104
	s_add_u32 s95, s86, 16
	v_add_u32_e32 v143, s95, v105
	v_add_u32_e32 v200, 0xffffe3f0, v143
	v_and_b32_e32 v201, 32, v200
	v_lshlrev_b32_e32 v201, 2, v201
	v_and_b32_e32 v200, 31, v200
	v_add_u32_e32 v200, 0x1c00, v200
	v_add_u32_e32 v200, v200, v201
	v_mov_b32_e32 v202, 0x1c10
	v_cmp_gt_u32_e32 vcc, v202, v143
	v_add_u32_e32 v201, 32, v143
	s_nop 0
	v_cndmask_b32_e32 v203, v200, v201, vcc
	v_mad_u32_u24 v110, v203, s96, v104
	s_add_u32 s95, s86, 24
	v_add_u32_e32 v143, s95, v105
	v_add_u32_e32 v200, 0xffffe3f0, v143
	v_and_b32_e32 v201, 32, v200
	v_lshlrev_b32_e32 v201, 2, v201
	v_and_b32_e32 v200, 31, v200
	v_add_u32_e32 v200, 0x1c00, v200
	v_add_u32_e32 v200, v200, v201
	v_mov_b32_e32 v202, 0x1c10
	v_cmp_gt_u32_e32 vcc, v202, v143
	v_add_u32_e32 v201, 32, v143
	s_nop 0
	v_cndmask_b32_e32 v203, v200, v201, vcc
	v_mad_u32_u24 v140, v203, s96, v104
	s_branch .Lp9_rd_a

.Lp9_loop:
	ds_write_b32 v102, v150
	ds_write_b32 v102, v151 offset:264
	ds_write_b32 v102, v152 offset:528
	ds_write_b32 v102, v153 offset:792
	ds_write_b32 v102, v154 offset:1056
	ds_write_b32 v102, v155 offset:1320
	ds_write_b32 v102, v156 offset:1584
	ds_write_b32 v102, v157 offset:1848
	ds_write_b32 v102, v158 offset:2112
	ds_write_b32 v102, v159 offset:2376
	ds_write_b32 v102, v160 offset:2640
	ds_write_b32 v102, v161 offset:2904
	ds_write_b32 v102, v162 offset:3168
	ds_write_b32 v102, v163 offset:3432
	ds_write_b32 v102, v164 offset:3696
	ds_write_b32 v102, v165 offset:3960
	ds_write_b32 v102, v166 offset:4224
	ds_write_b32 v102, v167 offset:4488
	ds_write_b32 v102, v168 offset:4752
	ds_write_b32 v102, v169 offset:5016
	ds_write_b32 v102, v170 offset:5280
	ds_write_b32 v102, v171 offset:5544
	ds_write_b32 v102, v172 offset:5808
	ds_write_b32 v102, v173 offset:6072
	ds_write_b32 v102, v174 offset:6336
	ds_write_b32 v102, v175 offset:6600
	ds_write_b32 v102, v176 offset:6864
	ds_write_b32 v102, v177 offset:7128
	ds_write_b32 v102, v178 offset:7392
	ds_write_b32 v102, v179 offset:7656
	ds_write_b32 v102, v180 offset:7920
	ds_write_b32 v102, v181 offset:8184
	s_add_u32 s73, s73, 0x600
	s_cmp_lt_u32 s73, 0x4200
	s_cselect_b32 s64, 1, 0
	s_cbranch_scc0 .Lp9_nold
	s_add_u32 s72, s73, 0x4400
	s_cmp_lt_u32 s73, 0x2c00
	s_cbranch_scc1 .Lp9_mp_b
	s_add_u32 s72, s73, 0x5a00

.Lp9_nost3:
	s_cmp_eq_u32 s64, 0
	s_cbranch_scc1 .Lp9_done
	s_mov_b32 s97, s94
	s_lshl_b32 s95, s87, 1
	s_add_u32 s92, s78, s95
	s_addc_u32 s93, s79, 0
	s_mov_b32 s94, s91
	s_lshl_b32 s96, s80, 1
	v_mov_b32_e32 v142, s13
	s_cmp_eq_u32 s12, 0
	s_cbranch_scc1 .Lp9_r0_b
	s_cmp_eq_u32 s12, 1
	s_cbranch_scc1 .Lp9_r1_b
	s_cmp_lt_u32 s86, 0x1000
	s_cbranch_scc1 .Lp9_r3a_b
	s_cmp_lt_u32 s86, 0x1800
	s_cbranch_scc1 .Lp9_r0_b
	s_cmp_lt_u32 s86, 0x1c00
	s_cbranch_scc1 .Lp9_r3c_b
	s_add_u32 s95, s86, 0
	v_add_u32_e32 v143, s95, v105
	v_add_u32_e32 v200, 0xffffe3f0, v143
	v_and_b32_e32 v201, 32, v200
	v_lshlrev_b32_e32 v201, 2, v201
	v_and_b32_e32 v200, 31, v200
	v_add_u32_e32 v200, 0x1c00, v200
	v_add_u32_e32 v200, v200, v201
	v_mov_b32_e32 v202, 0x1c10
	v_cmp_gt_u32_e32 vcc, v202, v143
	v_add_u32_e32 v201, 32, v143
	s_nop 0
	v_cndmask_b32_e32 v203, v200, v201, vcc
	v_mad_u32_u24 v108, v203, s96, v104
	s_add_u32 s95, s86, 8
	v_add_u32_e32 v143, s95, v105
	v_add_u32_e32 v200, 0xffffe3f0, v143
	v_and_b32_e32 v201, 32, v200
	v_lshlrev_b32_e32 v201, 2, v201
	v_and_b32_e32 v200, 31, v200
	v_add_u32_e32 v200, 0x1c00, v200
	v_add_u32_e32 v200, v200, v201
	v_mov_b32_e32 v202, 0x1c10
	v_cmp_gt_u32_e32 vcc, v202, v143
	v_add_u32_e32 v201, 32, v143
	s_nop 0
	v_cndmask_b32_e32 v203, v200, v201, vcc
	v_mad_u32_u24 v109, v203, s96, v104
	s_add_u32 s95, s86, 16
	v_add_u32_e32 v143, s95, v105
	v_add_u32_e32 v200, 0xffffe3f0, v143
	v_and_b32_e32 v201, 32, v200
	v_lshlrev_b32_e32 v201, 2, v201
	v_and_b32_e32 v200, 31, v200
	v_add_u32_e32 v200, 0x1c00, v200
	v_add_u32_e32 v200, v200, v201
	v_mov_b32_e32 v202, 0x1c10
	v_cmp_gt_u32_e32 vcc, v202, v143
	v_add_u32_e32 v201, 32, v143
	s_nop 0
	v_cndmask_b32_e32 v203, v200, v201, vcc
	v_mad_u32_u24 v110, v203, s96, v104
	s_add_u32 s95, s86, 24
	v_add_u32_e32 v143, s95, v105
	v_add_u32_e32 v200, 0xffffe3f0, v143
	v_and_b32_e32 v201, 32, v200
	v_lshlrev_b32_e32 v201, 2, v201
	v_and_b32_e32 v200, 31, v200
	v_add_u32_e32 v200, 0x1c00, v200
	v_add_u32_e32 v200, v200, v201
	v_mov_b32_e32 v202, 0x1c10
	v_cmp_gt_u32_e32 vcc, v202, v143
	v_add_u32_e32 v201, 32, v143
	s_nop 0
	v_cndmask_b32_e32 v203, v200, v201, vcc
	v_mad_u32_u24 v140, v203, s96, v104
	s_branch .Lp9_rd_b

.Lp9_w2:
	s_waitcnt vmcnt(2)
	s_branch .Lp9_loop
.Lp9_done:
	s_mov_b64 exec, -1
.LBB0_1035:
	s_cmp_gt_i32 s69, 10
	s_cselect_b64 s[0:1], -1, 0
	s_and_b64 s[4:5], s[4:5], s[0:1]
	s_andn2_b64 vcc, exec, s[4:5]
	s_cbranch_vccnz .LBB0_1085
	s_waitcnt vmcnt(0)
	v_cmp_eq_u32_e32 vcc, 0, v146
	s_waitcnt vmcnt(0) lgkmcnt(0)
	s_barrier
	s_and_saveexec_b64 s[4:5], vcc
	s_cbranch_execz .LBB0_1084
	s_add_i32 s3, 0, 0x23fc0
	v_mov_b32_e32 v0, s3
	s_waitcnt vmcnt(0) expcnt(0) lgkmcnt(0)
	ds_read_b32 v2, v0
	s_add_i32 s3, 0, 0x23fc4
	v_mov_b32_e32 v0, s3
	ds_read_b32 v0, v0
	s_waitcnt lgkmcnt(1)
	v_cmp_ne_u32_e32 vcc, 0, v2
	s_cbranch_vccnz .LBB0_1052
	s_add_u32 s6, s30, 0x32200
	s_addc_u32 s7, s31, 0
	s_add_u32 s8, s30, 0x32400
	s_addc_u32 s9, s31, 0
	s_add_u32 s10, s30, 0x32500
	s_addc_u32 s11, s31, 0
	s_add_u32 s12, s30, 0x32600
	s_addc_u32 s13, s31, 0
	s_add_u32 s14, s30, 0x32700
	s_addc_u32 s15, s31, 0
	s_add_u32 s16, s30, 0x32800
	s_addc_u32 s17, s31, 0
	s_add_u32 s18, s30, 0x32900
	s_addc_u32 s19, s31, 0
	s_add_u32 s20, s30, 0x32a00
	s_addc_u32 s21, s31, 0
	s_add_u32 s22, s30, 0x32b00
	s_addc_u32 s23, s31, 0
	s_add_u32 s24, s30, 0x32c00
	s_addc_u32 s25, s31, 0
	s_add_u32 s26, s30, 0x32d00
	s_addc_u32 s27, s31, 0
	s_add_u32 s34, s30, 0x32e00
	s_addc_u32 s35, s31, 0
	s_add_u32 s36, s30, 0x32f00
	s_addc_u32 s37, s31, 0
	s_add_u32 s38, s30, 0x33000
	s_addc_u32 s39, s31, 0
	s_add_u32 s40, s30, 0x33100
	s_addc_u32 s41, s31, 0
	s_add_u32 s42, s30, 0x33200
	s_addc_u32 s43, s31, 0
	s_mul_i32 s3, s71, s85
	s_add_u32 s44, s30, 0x33300
	s_mul_i32 s3, s3, s70
	s_addc_u32 s45, s31, 0
	s_mov_b32 s33, 1
	v_mov_b32_e32 v16, 0
	s_branch .LBB0_1040
